# next-unit scheduling fast path for a 256-workgroup grid; M2 wave-0 scans via DPP
# baseline (speedup 1.0000x reference)
;     __host__ __device__ bool next(int i, Unit& u) const {
;         const long L = (long)i * G + c; if (L >= nwg) return false;
;         int wgid = (int)L; { const int q = nwg / NXCD, r = nwg % NXCD, xcd = wgid % NXCD, off = wgid / NXCD; wgid = (xcd < r ? xcd * (q + 1) : r * (q + 1) + (xcd - r) * q) + off; }
;         const int nig = WGM * nN, gid = wgid / nig, fm = gid * WGM, gsz = (nM - fm) < WGM ? (nM - fm) : WGM;
;         u.pm = fm + ((wgid % nig) % gsz); u.pn = (wgid % nig) / gsz; return true;
.LBB0_131:
	s_add_i32 s43, s43, 1
	s_mul_i32 s1, s43, s46
	s_mul_hi_u32 s4, s43, s47
	s_add_i32 s4, s4, s1
	s_mul_i32 s1, s43, s47
	s_add_u32 s28, s1, s86
	s_addc_u32 s29, s4, s80
	v_cmp_gt_i64_e32 vcc, s[28:29], v[134:135]
	v_cmp_lt_i64_e64 s[4:5], s[28:29], v[132:133]
	s_cbranch_vccnz .LBB0_133
	s_cmpk_eq_u32 s74, 0x100
	s_cbranch_scc0 .Lsch_p1
	s_add_i32 s14, s6, 4
	s_mov_b32 s26, s0
	s_branch .LBB0_133
.Lsch_p1:
	s_ashr_i32 s1, s28, 31
	s_lshr_b32 s1, s1, 29
	s_add_i32 s1, s28, s1
	s_ashr_i32 s7, s1, 3
	s_and_b32 s1, s1, -8
	s_sub_i32 s1, s28, s1
	s_cmp_lt_i32 s1, 0
	s_cselect_b32 s14, s81, 0xb0
	s_mul_i32 s1, s1, s14
	s_add_i32 s1, s1, s7
	s_mul_hi_i32 s7, s1, 0x2e8ba2e9
	s_lshr_b32 s14, s7, 31
	s_ashr_i32 s7, s7, 5
	s_add_i32 s7, s7, s14
	s_lshl_b32 s15, s7, 3
	s_sub_i32 s14, 64, s15
	s_min_i32 s26, s14, 8
	s_abs_i32 s14, s26
	v_cvt_f32_u32_e32 v0, s14
	s_sub_i32 s28, 0, s14
	s_mulk_i32 s7, 0xb0
	s_sub_i32 s1, s1, s7
	v_rcp_iflag_f32_e32 v0, v0
	s_abs_i32 s7, s1
	s_xor_b32 s27, s1, s26
	s_ashr_i32 s27, s27, 31
	v_mul_f32_e32 v0, 0x4f7ffffe, v0
	v_cvt_u32_f32_e32 v0, v0
	s_nop 0
	v_readfirstlane_b32 s29, v0
	s_mul_i32 s28, s28, s29
	s_mul_hi_u32 s28, s29, s28
	s_add_i32 s29, s29, s28
	s_mul_hi_u32 s28, s7, s29
	s_mul_i32 s29, s28, s14
	s_sub_i32 s7, s7, s29
	s_add_i32 s30, s28, 1
	s_sub_i32 s29, s7, s14
	s_cmp_ge_u32 s7, s14
	s_cselect_b32 s28, s30, s28
	s_cselect_b32 s7, s29, s7
	s_add_i32 s29, s28, 1
	s_cmp_ge_u32 s7, s14
	s_cselect_b32 s7, s29, s28
	s_xor_b32 s7, s7, s27
	s_sub_i32 s14, s7, s27
	s_mul_i32 s7, s14, s26
	s_sub_i32 s1, s1, s7
	s_add_i32 s26, s15, s1

;     __host__ __device__ bool next(int i, Unit& u) const {
;         const long L = (long)i * G + c; if (L >= nwg) return false;
;         int wgid = (int)L; { const int q = nwg / NXCD, r = nwg % NXCD, xcd = wgid % NXCD, off = wgid / NXCD; wgid = (xcd < r ? xcd * (q + 1) : r * (q + 1) + (xcd - r) * q) + off; }
;         const int nig = WGM * nN, gid = wgid / nig, fm = gid * WGM, gsz = (nM - fm) < WGM ? (nM - fm) : WGM;
;         u.pm = fm + ((wgid % nig) % gsz); u.pn = (wgid % nig) / gsz; return true;
.LBB0_461:
	s_add_i32 s40, s40, 1
	s_mul_i32 s10, s40, s43
	s_mul_hi_u32 s11, s40, s44
	s_add_i32 s11, s11, s10
	s_mul_i32 s10, s40, s44
	s_add_u32 s24, s10, s86
	s_addc_u32 s25, s11, s45
	v_mov_b64_e32 v[0:1], 0x2c0
	v_cmp_lt_i64_e64 s[10:11], s[24:25], v[0:1]
	v_mov_b64_e32 v[0:1], 0x2bf
	v_cmp_gt_i64_e32 vcc, s[24:25], v[0:1]
	s_cbranch_vccnz .LBB0_463
	s_cmpk_eq_u32 s74, 0x100
	s_cbranch_scc0 .Lsch_p3
	s_add_i32 s18, s28, 4
	s_mov_b32 s20, s12
	s_branch .LBB0_463
.Lsch_p3:
	s_ashr_i32 s13, s24, 31
	s_lshr_b32 s13, s13, 29
	s_add_i32 s13, s24, s13
	s_ashr_i32 s18, s13, 3
	s_and_b32 s13, s13, -8
	s_sub_i32 s13, s24, s13
	s_cmp_lt_i32 s13, 0
	s_movk_i32 s19, 0x59
	s_cselect_b32 s19, s19, 0x58
	s_mul_i32 s13, s13, s19
	s_add_i32 s13, s13, s18
	s_mul_hi_i32 s18, s13, 0x2e8ba2e9
	s_lshr_b32 s19, s18, 31
	s_ashr_i32 s18, s18, 4
	s_add_i32 s18, s18, s19
	s_lshl_b32 s19, s18, 3
	s_sub_i32 s20, 64, s19
	s_min_i32 s20, s20, 8
	s_abs_i32 s21, s20
	v_cvt_f32_u32_e32 v0, s21
	s_sub_i32 s25, 0, s21
	s_mulk_i32 s18, 0x58
	s_sub_i32 s13, s13, s18
	v_rcp_iflag_f32_e32 v0, v0
	s_abs_i32 s18, s13
	s_xor_b32 s24, s13, s20
	s_ashr_i32 s24, s24, 31
	v_mul_f32_e32 v0, 0x4f7ffffe, v0
	v_cvt_u32_f32_e32 v0, v0
	s_nop 0
	v_readfirstlane_b32 s26, v0
	s_mul_i32 s25, s25, s26
	s_mul_hi_u32 s25, s26, s25
	s_add_i32 s26, s26, s25
	s_mul_hi_u32 s25, s18, s26
	s_mul_i32 s26, s25, s21
	s_sub_i32 s18, s18, s26
	s_add_i32 s27, s25, 1
	s_sub_i32 s26, s18, s21
	s_cmp_ge_u32 s18, s21
	s_cselect_b32 s25, s27, s25
	s_cselect_b32 s18, s26, s18
	s_add_i32 s26, s25, 1
	s_cmp_ge_u32 s18, s21
	s_cselect_b32 s18, s26, s25
	s_xor_b32 s18, s18, s24
	s_sub_i32 s18, s18, s24
	s_mul_i32 s20, s18, s20
	s_sub_i32 s13, s13, s20
	s_add_i32 s20, s19, s13

; __device__ __forceinline__ void m2_phase(const Params& p, unsigned char* ldsg, int G) {
;     ...
;             const f32x4 g4 = *(const f32x4*)(GARR + h * NCH + 4 * lane), a4 = *(const f32x4*)(AMAXARR + h * NCH + 4 * lane);
;             const float tot = (g4[0] + g4[1]) + (g4[2] + g4[3]);
;             const float inc = wave_incl_sum(tot, lane); const float pbase = inc - tot;
;             float P[5]; P[0] = pbase; P[1] = P[0] + g4[0]; P[2] = P[1] + g4[1]; P[3] = P[2] + g4[2]; P[4] = P[3] + g4[3];
;             float z[4];
; #pragma unroll
;             for (int i = 0; i < 4; ++i) z[i] = a4[i] - P[i + 1];
;             const float zl = fmaxf(fmaxf(z[0], z[1]), fmaxf(z[2], z[3]));
;             const float zi = wave_incl_max(zl, lane); float zprev = __shfl_up(zi, 1); if (lane == 0) zprev = 0.f; zprev = fmaxf(zprev, 0.f);
.LBB0_1033:
	s_lshl_b32 s20, s2, 8
	s_add_i32 s20, s20, s3
	s_ashr_i32 s21, s20, 31
	s_lshl_b64 s[20:21], s[20:21], 9
	v_lshl_add_u64 v[42:43], v[38:39], 0, s[20:21]
	v_add_co_u32_e32 v0, vcc, s46, v42
	global_load_dwordx2 v[90:91], v[42:43], off
	global_load_dwordx2 v[88:89], v[42:43], off offset:512
	global_load_dwordx2 v[86:87], v[42:43], off offset:1024
	global_load_dwordx2 v[84:85], v[42:43], off offset:1536
	global_load_dwordx2 v[80:81], v[42:43], off offset:2048
	global_load_dwordx2 v[78:79], v[42:43], off offset:2560
	global_load_dwordx2 v[76:77], v[42:43], off offset:3072
	global_load_dwordx2 v[74:75], v[42:43], off offset:3584
	v_addc_co_u32_e32 v1, vcc, 0, v43, vcc
	v_add_co_u32_e32 v2, vcc, s35, v42
	s_ashr_i32 s87, s2, 6
	s_nop 0
	v_addc_co_u32_e32 v3, vcc, 0, v43, vcc
	v_add_co_u32_e32 v4, vcc, 0x3000, v42
	global_load_dwordx2 v[72:73], v[0:1], off offset:512
	global_load_dwordx2 v[70:71], v[0:1], off offset:1024
	global_load_dwordx2 v[66:67], v[0:1], off offset:1536
	global_load_dwordx2 v[62:63], v[0:1], off offset:2048
	global_load_dwordx2 v[22:23], v[2:3], off
	global_load_dwordx2 v[20:21], v[2:3], off offset:512
	global_load_dwordx2 v[18:19], v[2:3], off offset:1024
	global_load_dwordx2 v[16:17], v[2:3], off offset:1536
	global_load_dwordx2 v[58:59], v[2:3], off offset:2048
	global_load_dwordx2 v[56:57], v[2:3], off offset:2560
	global_load_dwordx2 v[26:27], v[2:3], off offset:3072
	global_load_dwordx2 v[24:25], v[2:3], off offset:3584
	v_addc_co_u32_e32 v5, vcc, 0, v43, vcc
	global_load_dwordx2 v[68:69], v[0:1], off offset:2560
	global_load_dwordx2 v[64:65], v[0:1], off offset:3072
	global_load_dwordx2 v[60:61], v[0:1], off offset:3584
	global_load_dwordx2 v[30:31], v[4:5], off
	global_load_dwordx2 v[28:29], v[4:5], off offset:512
	global_load_dwordx2 v[54:55], v[4:5], off offset:1024
	global_load_dwordx2 v[52:53], v[4:5], off offset:1536
	global_load_dwordx2 v[50:51], v[4:5], off offset:2048
	global_load_dwordx2 v[82:83], v[2:3], off offset:-4096
	global_load_dwordx2 v[44:45], v[4:5], off offset:2560
	global_load_dwordx2 v[46:47], v[4:5], off offset:3072
	global_load_dwordx2 v[136:137], v[4:5], off offset:3584
	s_andn2_b64 vcc, exec, s[22:23]
	s_and_b32 s48, s2, 63
	s_cbranch_vccnz .LBB0_1042
	s_lshl_b32 s30, s87, 8
	s_ashr_i32 s31, s30, 31
	s_lshl_b64 s[20:21], s[30:31], 2
	v_lshl_add_u64 v[0:1], v[34:35], 0, s[20:21]
	global_load_dwordx4 v[4:7], v[0:1], off
	v_lshl_add_u64 v[0:1], v[36:37], 0, s[20:21]
	global_load_dwordx4 v[0:3], v[0:1], off
	v_add_u32_e32 v10, -1, v169
	v_add_u32_e32 v11, -2, v169
	s_cmp_eq_u32 s48, 0
	s_cselect_b64 s[46:47], -1, 0
	s_cmp_lg_u32 s48, 0
	s_cselect_b64 s[20:21], -1, 0
	s_waitcnt vmcnt(1)
	v_add_f32_e32 v8, v4, v5
	v_add_f32_e32 v9, v6, v7
	v_add_f32_e32 v8, v8, v9
	v_and_b32_e32 v9, 64, v169
	v_cmp_lt_i32_e32 vcc, v10, v9
	s_nop 1
	v_cndmask_b32_e32 v10, v10, v169, vcc
	v_lshlrev_b32_e32 v33, 2, v10
	v_mov_b32_e32 v10, v8
	s_nop 1
	v_add_f32_dpp v10, v10, v10 row_shr:1 row_mask:0xf bank_mask:0xf bound_ctrl:0
	s_nop 1
	v_add_f32_dpp v10, v10, v10 row_shr:2 row_mask:0xf bank_mask:0xf bound_ctrl:0
	s_nop 1
	v_add_f32_dpp v10, v10, v10 row_shr:4 row_mask:0xf bank_mask:0xf bound_ctrl:0
	s_nop 1
	v_add_f32_dpp v10, v10, v10 row_shr:8 row_mask:0xf bank_mask:0xf bound_ctrl:0
	s_nop 1
	v_add_f32_dpp v10, v10, v10 row_bcast:15 row_mask:0xa bank_mask:0xf
	s_nop 1
	v_add_f32_dpp v10, v10, v10 row_bcast:31 row_mask:0xc bank_mask:0xf
	v_sub_f32_e32 v98, v10, v8
	v_add_f32_e32 v99, v4, v98
	v_add_f32_e32 v14, v5, v99
	v_add_f32_e32 v12, v6, v14
	v_add_f32_e32 v10, v7, v12
	s_waitcnt vmcnt(0)
	v_sub_f32_e32 v13, v2, v12
	v_sub_f32_e32 v11, v3, v10
	v_sub_f32_e32 v100, v0, v99
	v_sub_f32_e32 v15, v1, v14
	v_max_f32_e32 v8, v13, v11
	v_max3_f32 v8, v100, v15, v8
	s_nop 1
	v_max_f32_dpp v8, v8, v8 row_shr:1 row_mask:0xf bank_mask:0xf
	s_nop 1
	v_max_f32_dpp v8, v8, v8 row_shr:2 row_mask:0xf bank_mask:0xf
	s_nop 1
	v_max_f32_dpp v8, v8, v8 row_shr:4 row_mask:0xf bank_mask:0xf
	s_nop 1
	v_max_f32_dpp v8, v8, v8 row_shr:8 row_mask:0xf bank_mask:0xf
	s_nop 1
	v_max_f32_dpp v8, v8, v8 row_bcast:15 row_mask:0xa bank_mask:0xf
	s_nop 1
	v_max_f32_dpp v8, v8, v8 row_bcast:31 row_mask:0xc bank_mask:0xf
	ds_bpermute_b32 v8, v33, v8
	s_waitcnt lgkmcnt(0)
	v_max_f32_e32 v8, v8, v8
	v_max_f32_e32 v8, 0, v8
	v_cndmask_b32_e64 v9, v8, 0, s[8:9]
	v_add_f32_e32 v95, v98, v9
	v_max_f32_e32 v94, v9, v100
	v_add_f32_e32 v33, v99, v94
	v_add_f32_e32 v4, v4, v95
	v_sub_f32_e32 v4, v4, v33
	v_mul_f32_e32 v9, 0x3fb8aa3b, v4
	v_fma_f32 v96, v4, s36, -v9
	v_rndne_f32_e32 v97, v9
	v_fmac_f32_e32 v96, 0x32a5705f, v4
	v_sub_f32_e32 v9, v9, v97
	v_add_f32_e32 v9, v9, v96
	v_exp_f32_e32 v9, v9
	v_cvt_i32_f32_e32 v96, v97
	v_cmp_ngt_f32_e32 vcc, s37, v4
	v_sub_f32_e32 v0, v0, v33
	v_or_b32_e32 v8, s30, v48
	v_ldexp_f32 v9, v9, v96
	v_cndmask_b32_e32 v9, 0, v9, vcc
	v_cmp_nlt_f32_e32 vcc, s38, v4
	s_nop 1
	v_cndmask_b32_e32 v4, v171, v9, vcc
	v_mul_f32_e32 v9, 0x3fb8aa3b, v0
	v_fma_f32 v96, v0, s36, -v9
	v_rndne_f32_e32 v97, v9
	v_fmac_f32_e32 v96, 0x32a5705f, v0
	v_sub_f32_e32 v9, v9, v97
	v_add_f32_e32 v9, v9, v96
	v_exp_f32_e32 v9, v9
	v_cvt_i32_f32_e32 v96, v97
	v_cmp_ngt_f32_e32 vcc, s37, v0
	v_ldexp_f32 v9, v9, v96
	s_nop 0
	v_cndmask_b32_e32 v9, 0, v9, vcc
	v_cmp_nlt_f32_e32 vcc, s38, v0
	s_nop 1
	v_cndmask_b32_e32 v0, v171, v9, vcc
	s_and_b64 vcc, exec, s[20:21]
	ds_write2st64_b32 v248, v4, v0 offset1:4
	s_cbranch_vccnz .LBB0_1036
	v_ashrrev_i32_e32 v9, 31, v8
	v_lshl_add_u64 v[96:97], v[8:9], 2, s[0:1]
	global_store_dword v[96:97], v95, off

;     __host__ __device__ bool next(int i, Unit& u) const {
;         const long L = (long)i * G + c; if (L >= nwg) return false;
;         int wgid = (int)L; { const int q = nwg / NXCD, r = nwg % NXCD, xcd = wgid % NXCD, off = wgid / NXCD; wgid = (xcd < r ? xcd * (q + 1) : r * (q + 1) + (xcd - r) * q) + off; }
;         const int nig = WGM * nN, gid = wgid / nig, fm = gid * WGM, gsz = (nM - fm) < WGM ? (nM - fm) : WGM;
;         u.pm = fm + ((wgid % nig) % gsz); u.pn = (wgid % nig) / gsz; return true;
.LBB0_1319:
	s_add_i32 s37, s37, 1
	s_mul_i32 s1, s37, s40
	s_mul_hi_u32 s8, s37, s41
	s_add_i32 s8, s8, s1
	s_mul_i32 s1, s37, s41
	s_add_u32 s20, s1, s86
	s_addc_u32 s21, s8, s42
	v_cmp_gt_i64_e32 vcc, s[20:21], v[134:135]
	v_cmp_lt_i64_e64 s[8:9], s[20:21], v[132:133]
	s_cbranch_vccnz .LBB0_1321
	s_cmpk_eq_u32 s74, 0x100
	s_cbranch_scc0 .Lsch_p8
	s_add_i32 s16, s10, 4
	s_mov_b32 s18, s0
	s_branch .LBB0_1321
.Lsch_p8:
	s_ashr_i32 s1, s20, 31
	s_lshr_b32 s1, s1, 29
	s_add_i32 s1, s20, s1
	s_ashr_i32 s11, s1, 3
	s_and_b32 s1, s1, -8
	s_sub_i32 s1, s20, s1
	s_cmp_lt_i32 s1, 0
	s_cselect_b32 s16, s43, 0xb0
	s_mul_i32 s1, s1, s16
	s_add_i32 s1, s1, s11
	s_mul_hi_i32 s11, s1, 0x2e8ba2e9
	s_lshr_b32 s16, s11, 31
	s_ashr_i32 s11, s11, 5
	s_add_i32 s11, s11, s16
	s_lshl_b32 s17, s11, 3
	s_sub_i32 s16, 64, s17
	s_min_i32 s18, s16, 8
	s_abs_i32 s16, s18
	v_cvt_f32_u32_e32 v0, s16
	s_sub_i32 s20, 0, s16
	s_mulk_i32 s11, 0xb0
	s_sub_i32 s1, s1, s11
	v_rcp_iflag_f32_e32 v0, v0
	s_abs_i32 s11, s1
	s_xor_b32 s19, s1, s18
	s_ashr_i32 s19, s19, 31
	v_mul_f32_e32 v0, 0x4f7ffffe, v0
	v_cvt_u32_f32_e32 v0, v0
	s_nop 0
	v_readfirstlane_b32 s21, v0
	s_mul_i32 s20, s20, s21
	s_mul_hi_u32 s20, s21, s20
	s_add_i32 s21, s21, s20
	s_mul_hi_u32 s20, s11, s21
	s_mul_i32 s21, s20, s16
	s_sub_i32 s11, s11, s21
	s_add_i32 s22, s20, 1
	s_sub_i32 s21, s11, s16
	s_cmp_ge_u32 s11, s16
	s_cselect_b32 s20, s22, s20
	s_cselect_b32 s11, s21, s11
	s_add_i32 s21, s20, 1
	s_cmp_ge_u32 s11, s16
	s_cselect_b32 s11, s21, s20
	s_xor_b32 s11, s11, s19
	s_sub_i32 s16, s11, s19
	s_mul_i32 s11, s16, s18
	s_sub_i32 s1, s1, s11
	s_add_i32 s18, s17, s1
